# P0 workgroup 0: the 22 absmax loads issued at the very start of P0 (into v118-139), reduced at the end; on top of v91
# speedup vs baseline: 1.0075x; 1.0006x over previous
; #define LAS __attribute__((address_space(3)))
; __device__ __forceinline__ int lane_id() { int l; asm volatile("v_mbcnt_lo_u32_b32 %0, -1, 0\n\tv_mbcnt_hi_u32_b32 %0, -1, %0" : "=v"(l)); return l; }
; __global__ void __launch_bounds__(NWAVES * 64, 2) fwd_kernel(Args args) {
;     ...
;     const float* x = args.in[0]; const float* norm_gain = args.in[1];
;     bf16* XB = (bf16*)(ws + WS_XB);
;     float* rstd1 = (float*)(ws + WS_RSTD1); float* part2 = (float*)(ws + WS_PART2);
; _Pragma("unroll 1") for (int rep_ = 0; rep_ < NREP(0); ++rep_) {
;     if (IN(0)) {
;         int tid0_ = F.wave * 64 + lane_id(); asm volatile("" : "+v"(tid0_)); F.tid = tid0_; F.lane = tid0_ & 63;
;         LAS float* scr = (LAS float*)(F.lds + RING_OFF + F.wave * 16384);
;         const int gw = F.vcu * NWAVES + F.wave, NGW = F.G * NWAVES;
;         constexpr int I_AIN = (DM / 64) * (NA_IN / 32), I_O = (DM / 64) * (DM / 32), I_BIN = (DM / 64) * (NB_IN / 32);
;         constexpr int NITEMS = I_AIN + I_O + I_BIN + I_O;
;     ...
;             const float ca = 64.0f * QSCALE * att::wg_absmax(args.in[4], 192, scr0, F.tid) * att::wg_absmax(args.in[5], 192, scr0, F.tid) + LOG2E * att::wg_absmax(args.in[6], 48 * 32, scr0, F.tid);
;             const float cb = 64.0f * QSCALE * att::wg_absmax(args.in[9], 64, scr0, F.tid) * att::wg_absmax(args.in[10], 64, scr0, F.tid) + LOG2E * att::wg_absmax(args.in[11], NH * 15 * 31, scr0, F.tid);
.LBB0_10:
	v_writelane_b32 v253, s12, 6
	s_cmp_lt_i32 s66, 1
	s_cselect_b64 s[0:1], -1, 0
	v_writelane_b32 v253, s13, 7
	s_cmp_gt_i32 s67, 0
	v_writelane_b32 v253, s14, 8
	s_cselect_b64 s[4:5], -1, 0
	v_writelane_b32 v253, s15, 9
	s_and_b64 s[0:1], s[0:1], s[4:5]
	v_writelane_b32 v253, s16, 10
	s_add_u32 s30, s42, 0x2200000
	v_writelane_b32 v253, s17, 11
	s_addc_u32 s31, s43, 0
	v_writelane_b32 v253, s18, 12
	s_add_u32 s4, s42, 0x1a00000
	v_writelane_b32 v253, s19, 13
	s_addc_u32 s5, s43, 0
	v_writelane_b32 v253, s4, 14
	s_mov_b32 s89, 0
	s_nop 0
	v_writelane_b32 v253, s5, 15
	s_add_u32 s4, s42, 0x1800000
	s_addc_u32 s5, s43, 0
	v_writelane_b32 v253, s4, 16
	s_nop 1
	v_writelane_b32 v253, s5, 17
	s_add_u32 s4, s42, 0x400000
	s_addc_u32 s5, s43, 0
	v_writelane_b32 v253, s4, 18
	s_nop 1
	v_writelane_b32 v253, s5, 19
	s_add_u32 s4, s42, 0x180000
	s_addc_u32 s5, s43, 0
	v_writelane_b32 v253, s4, 20
	s_cmp_eq_u32 s6, 15
	s_nop 0
	v_writelane_b32 v253, s5, 21
	s_cselect_b64 s[4:5], -1, 0
	v_writelane_b32 v253, s4, 22
	s_cmp_eq_u32 s6, 14
	s_nop 0
	v_writelane_b32 v253, s5, 23
	s_cselect_b64 s[4:5], -1, 0
	v_writelane_b32 v253, s4, 24
	s_cmp_eq_u32 s6, 13
	s_nop 0
	v_writelane_b32 v253, s5, 25
	s_cselect_b64 s[4:5], -1, 0
	v_writelane_b32 v253, s4, 26
	s_cmp_eq_u32 s6, 12
	s_nop 0
	v_writelane_b32 v253, s5, 27
	s_cselect_b64 s[4:5], -1, 0
	v_writelane_b32 v253, s4, 28
	s_cmp_eq_u32 s6, 11
	s_nop 0
	v_writelane_b32 v253, s5, 29
	s_cselect_b64 s[4:5], -1, 0
	v_writelane_b32 v253, s4, 30
	s_cmp_eq_u32 s6, 10
	s_nop 0
	v_writelane_b32 v253, s5, 31
	s_cselect_b64 s[4:5], -1, 0
	v_writelane_b32 v253, s4, 32
	s_cmp_eq_u32 s6, 9
	s_nop 0
	v_writelane_b32 v253, s5, 33
	s_cselect_b64 s[4:5], -1, 0
	v_writelane_b32 v253, s4, 34
	s_cmp_eq_u32 s6, 8
	s_nop 0
	v_writelane_b32 v253, s5, 35
	s_cselect_b64 s[4:5], -1, 0
	v_writelane_b32 v253, s4, 36
	s_cmp_eq_u32 s6, 7
	s_nop 0
	v_writelane_b32 v253, s5, 37
	s_cselect_b64 s[4:5], -1, 0
	v_writelane_b32 v253, s4, 38
	s_cmp_eq_u32 s6, 6
	s_nop 0
	v_writelane_b32 v253, s5, 39
	s_cselect_b64 s[4:5], -1, 0
	v_writelane_b32 v253, s4, 40
	s_cmp_eq_u32 s6, 5
	s_nop 0
	v_writelane_b32 v253, s5, 41
	s_cselect_b64 s[4:5], -1, 0
	v_writelane_b32 v253, s4, 42
	s_cmp_eq_u32 s6, 4
	s_nop 0
	v_writelane_b32 v253, s5, 43
	s_cselect_b64 s[4:5], -1, 0
	v_writelane_b32 v253, s4, 44
	s_cmp_eq_u32 s6, 3
	s_nop 0
	v_writelane_b32 v253, s5, 45
	s_cselect_b64 s[4:5], -1, 0
	v_writelane_b32 v253, s4, 46
	s_cmp_eq_u32 s6, 2
	s_nop 0
	v_writelane_b32 v253, s5, 47
	s_cselect_b64 s[4:5], -1, 0
	v_writelane_b32 v253, s4, 48
	s_cmp_eq_u32 s6, 1
	s_nop 0
	v_writelane_b32 v253, s5, 49
	s_cselect_b64 s[4:5], -1, 0
	v_writelane_b32 v253, s4, 50
	s_cmp_eq_u32 s6, 0
	s_nop 0
	v_writelane_b32 v253, s5, 51
	s_cselect_b64 s[4:5], -1, 0
	v_writelane_b32 v253, s4, 52
	s_and_b64 vcc, exec, s[0:1]
	s_nop 0
	v_writelane_b32 v253, s5, 53
	s_lshl_b32 s4, s6, 6
	v_writelane_b32 v253, s4, 54
	s_cbranch_vccz .LBB0_185
	s_lshl_b32 s14, s60, 3
	v_mbcnt_lo_u32_b32 v0, -1, 0
	v_mbcnt_hi_u32_b32 v0, -1, v0
	s_add_i32 s14, s14, s2
	v_add_u32_e32 v64, s65, v0
	s_cmp_lg_u32 s87, 0
	s_cbranch_scc1 .Labm_skip
	v_readlane_b32 s96, v253, 8
	v_readlane_b32 s97, v253, 9
	v_readlane_b32 s98, v253, 10
	v_readlane_b32 s99, v253, 11
	v_readlane_b32 s100, v253, 12
	v_readlane_b32 s101, v253, 13
	v_mov_b32_e32 v118, 0
	v_mov_b32_e32 v119, 0
	v_mov_b32_e32 v120, 0
	v_mov_b32_e32 v121, 0
	v_mov_b32_e32 v122, 0
	v_mov_b32_e32 v123, 0
	v_mov_b32_e32 v124, 0
	v_mov_b32_e32 v125, 0
	v_mov_b32_e32 v126, 0
	v_mov_b32_e32 v127, 0
	v_mov_b32_e32 v128, 0
	v_mov_b32_e32 v129, 0
	v_mov_b32_e32 v130, 0
	v_mov_b32_e32 v131, 0
	v_mov_b32_e32 v132, 0
	v_mov_b32_e32 v133, 0
	v_mov_b32_e32 v134, 0
	v_mov_b32_e32 v135, 0
	v_mov_b32_e32 v136, 0
	v_mov_b32_e32 v137, 0
	v_mov_b32_e32 v138, 0
	v_mov_b32_e32 v139, 0
	v_lshlrev_b32_e32 v140, 2, v64
	v_cmp_gt_u32_e32 vcc, 0xc0, v64
	s_and_saveexec_b64 s[94:95], vcc
	global_load_dword v118, v140, s[52:53]
	global_load_dword v119, v140, s[54:55]
	s_mov_b64 exec, s[94:95]
	global_load_dword v120, v140, s[56:57]
	global_load_dword v121, v140, s[56:57] offset:2048
	v_add_u32_e32 v141, 0x1000, v140
	global_load_dword v122, v141, s[56:57]
	v_cmp_gt_u32_e32 vcc, 64, v64
	s_and_saveexec_b64 s[94:95], vcc
	global_load_dword v123, v140, s[96:97]
	global_load_dword v124, v140, s[98:99]
	s_mov_b64 exec, s[94:95]
	v_mov_b32_e32 v141, v140
	global_load_dword v125, v141, s[100:101]
	global_load_dword v126, v141, s[100:101] offset:2048
	v_add_u32_e32 v141, 0x1000, v141
	global_load_dword v127, v141, s[100:101]
	global_load_dword v128, v141, s[100:101] offset:2048
	v_add_u32_e32 v141, 0x1000, v141
	global_load_dword v129, v141, s[100:101]
	global_load_dword v130, v141, s[100:101] offset:2048
	v_add_u32_e32 v141, 0x1000, v141
	global_load_dword v131, v141, s[100:101]
	global_load_dword v132, v141, s[100:101] offset:2048
	v_add_u32_e32 v141, 0x1000, v141
	global_load_dword v133, v141, s[100:101]
	global_load_dword v134, v141, s[100:101] offset:2048
	v_add_u32_e32 v141, 0x1000, v141
	global_load_dword v135, v141, s[100:101]
	global_load_dword v136, v141, s[100:101] offset:2048
	v_add_u32_e32 v141, 0x1000, v141
	global_load_dword v137, v141, s[100:101]
	global_load_dword v138, v141, s[100:101] offset:2048
	v_add_u32_e32 v141, 0x1000, v141
	v_cmp_gt_u32_e32 vcc, 0x110, v64
	s_and_saveexec_b64 s[94:95], vcc
	global_load_dword v139, v141, s[100:101]
	s_mov_b64 exec, s[94:95]
; #define LAS __attribute__((address_space(3)))
; #define LDS_WAIT() asm volatile("s_waitcnt lgkmcnt(0)" ::: "memory")
; template <bool F16 = false>
; __device__ __forceinline__ void p0_transpose_item(const float* W, int K, int N, bf16* WT, const float* gk, LAS float* scr, int item, int lane) {
;     const int nblk = N / 32, kb = item / nblk, nb = item % nblk, k0 = 64 * kb, n0 = 32 * nb;
;     float wv[32];
; #pragma unroll
;     for (int i = 0; i < 32; ++i) { const int kk = 2 * i + (lane >> 5); wv[i] = __builtin_nontemporal_load(W + (size_t)(k0 + kk) * N + n0 + (lane & 31)); }
; #pragma unroll
;     for (int i = 0; i < 32; ++i) { const int kk = 2 * i + (lane >> 5); const float gsc = gk ? gk[k0 + kk] : 1.0f; scr[kk * 33 + (lane & 31)] = wv[i] * gsc; }
;     LDS_WAIT(); asm volatile("" ::: "memory");
;     const int c = lane & 7;
; #pragma unroll
;     for (int j = 0; j < 4; ++j) { const int n = (lane >> 3) + 8 * j; const LAS float* s = scr + (8 * c) * 33 + n;
;         v4u o;
; __global__ void __launch_bounds__(NWAVES * 64, 2) fwd_kernel(Args args) {
;     ...
;         for (int it = gw; it < NITEMS; it += NGW) {
;             int r = it;
;             if (r < I_AIN) { p0_transpose_item(args.in[2], DM, NA_IN, (bf16*)(ws + WS_WAIN), norm_gain, scr, r, F.lane); continue; } r -= I_AIN;
;             if (r < I_O) { p0_transpose_item(args.in[3], DM, DM, (bf16*)(ws + WS_WAOUT), nullptr, scr, r, F.lane); continue; } r -= I_O;
;             if (r < I_BIN) { p0_transpose_item<true>(args.in[7], DM, NB_IN, (bf16*)(ws + WS_WBIN), norm_gain + DM, scr, r, F.lane); continue; } r -= I_BIN;
;             p0_transpose_item(args.in[8], DM, DM, (bf16*)(ws + WS_WBOUT), nullptr, scr, r, F.lane);
;         }
.Labm_skip:
	s_cmpk_gt_i32 s14, 0x1fff
	v_and_b32_e32 v72, 63, v64
	v_lshlrev_b32_e32 v0, 3, v72
	s_cbranch_scc1 .LBB0_58
	s_lshl_b32 s0, s2, 14
	v_lshrrev_b32_e32 v25, 3, v72
	v_and_b32_e32 v3, 56, v0
	s_add_i32 s0, s0, 0
	v_lshrrev_b32_e32 v2, 5, v72
	v_mul_u32_u24_e32 v8, 0x84, v3
	v_lshlrev_b32_e32 v12, 1, v3
	v_lshlrev_b32_e32 v3, 2, v25
	s_movk_i32 s2, 0x84
	v_add3_u32 v26, s0, v8, v3
	v_or_b32_e32 v30, 2, v2
	v_mov_b32_e32 v3, 0x108
	v_mad_u32_u24 v14, v30, s2, v3
	v_mov_b32_e32 v3, 0x318
	v_mov_b32_e32 v5, 0
	v_mad_u32_u24 v15, v30, s2, v3
	v_mov_b32_e32 v3, 0x528
	v_readlane_b32 s8, v253, 14
	s_lshl_b32 s15, s3, 3
	v_mov_b32_e32 v13, v5
	v_mad_u32_u24 v16, v30, s2, v3
	v_mov_b32_e32 v3, 0x630
	v_readlane_b32 s9, v253, 15
	s_add_u32 s4, s46, 0x1000
	v_mad_u32_u24 v17, v30, s2, v3
	v_mov_b32_e32 v3, 0x738
	v_lshl_add_u64 v[8:9], s[8:9], 0, v[12:13]
	v_readlane_b32 s8, v253, 16
	s_addc_u32 s5, s47, 0
	v_lshlrev_b32_e32 v1, 2, v64
	v_mad_u32_u24 v18, v30, s2, v3
	v_mov_b32_e32 v3, 0x948
	v_readlane_b32 s9, v253, 17
	s_cmp_lg_u64 s[46:47], 0
	v_and_b32_e32 v4, 0x7c, v1
	v_mad_u32_u24 v19, v30, s2, v3
	v_mov_b32_e32 v3, 0xb58
	v_lshl_add_u64 v[10:11], s[8:9], 0, v[12:13]
	v_readlane_b32 s8, v253, 18
	v_readlane_b32 s68, v253, 6
	s_cselect_b64 s[6:7], -1, 0
	v_add_u32_e32 v1, s0, v4
	v_mad_u32_u24 v20, v30, s2, v3
	v_mov_b32_e32 v3, 0xc60
	v_readlane_b32 s9, v253, 19
	s_lshl_b32 s0, s14, 1
	v_readlane_b32 s69, v253, 7
	s_mov_b32 s1, 0
	v_mul_u32_u24_e32 v24, 0x84, v2
	v_lshl_add_u64 v[6:7], s[30:31], 0, v[12:13]
	v_or_b32_e32 v27, 8, v25
	v_or_b32_e32 v28, 16, v25
	v_or_b32_e32 v29, 24, v25
	v_mul_u32_u24_e32 v31, 0x84, v30
	v_or_b32_e32 v32, 4, v2
	v_or_b32_e32 v33, 6, v2
	v_or_b32_e32 v34, 8, v2
	v_or_b32_e32 v35, 10, v2
	v_or_b32_e32 v36, 12, v2
	v_or_b32_e32 v37, 14, v2
	v_or_b32_e32 v38, 16, v2
	v_or_b32_e32 v39, 18, v2
	v_or_b32_e32 v40, 20, v2
	v_or_b32_e32 v41, 22, v2
	v_or_b32_e32 v42, 24, v2
	v_or_b32_e32 v43, 26, v2
	v_mad_u32_u24 v44, v30, s2, v3
	v_or_b32_e32 v45, 28, v2
	v_or_b32_e32 v46, 30, v2
	v_or_b32_e32 v47, 32, v2
	v_or_b32_e32 v48, 34, v2
	v_or_b32_e32 v49, 36, v2
	v_or_b32_e32 v50, 38, v2
	v_or_b32_e32 v51, 40, v2
	v_or_b32_e32 v52, 42, v2
	v_or_b32_e32 v53, 44, v2
	v_or_b32_e32 v54, 46, v2
	v_or_b32_e32 v55, 48, v2
	v_or_b32_e32 v56, 50, v2
	v_or_b32_e32 v57, 52, v2
	v_or_b32_e32 v58, 54, v2
	v_lshl_add_u64 v[12:13], s[8:9], 0, v[12:13]
	v_mov_b32_e32 v3, v5
	s_lshl_b32 s16, s14, 5
	s_lshl_b32 s17, s3, 8
	s_add_i32 s18, s0, 0x1c400
	s_lshl_b32 s19, s3, 4
	s_mov_b32 s20, 0xa000
	s_movk_i32 s21, 0x7fff
	s_mov_b32 s22, 0xffff0000
	v_add_u32_e32 v59, v1, v17
	v_add_u32_e32 v60, v1, v14
	v_add_u32_e32 v61, v1, v16
	v_add_u32_e32 v62, v1, v19
	v_add_u32_e32 v63, v1, v15
	v_add_u32_e32 v65, v1, v18
	v_add_u32_e32 v66, v1, v20
	s_mov_b32 s23, s14
	v_or_b32_e32 v67, 56, v2
	v_or_b32_e32 v68, 58, v2
	v_or_b32_e32 v69, 60, v2
	v_or_b32_e32 v70, 62, v2
	v_lshl_add_u64 v[14:15], s[68:69], 0, v[4:5]
	v_lshl_add_u64 v[16:17], s[58:59], 0, v[4:5]
	v_lshl_add_u64 v[18:19], s[50:51], 0, v[4:5]
	v_lshl_add_u64 v[20:21], s[48:49], 0, v[4:5]
	v_readlane_b32 s70, v253, 8
	v_readlane_b32 s71, v253, 9
	v_readlane_b32 s72, v253, 10
	v_readlane_b32 s73, v253, 11
	v_readlane_b32 s74, v253, 12
	v_readlane_b32 s75, v253, 13
	s_branch .LBB0_16

; __device__ __forceinline__ float wave_max(float v) { v = fmaxf(v, dpp_mov<0xB1>(v)); v = fmaxf(v, dpp_mov<0x4E>(v)); v = fmaxf(v, dpp_mov<0x141>(v)); v = fmaxf(v, dpp_mov<0x140>(v)); v = max_x16(v); return max_x32(v); }
; #define LAS __attribute__((address_space(3)))
; __device__ __forceinline__ float wg_absmax(const float* p, int n, LAS float* scr, int tid) {
;     float m = 0.f;
;     for (int i = tid; i < n; i += NWAVES * 64) m = fmaxf(m, fabsf(p[i]));
;     m = wave_max(m);
;     __syncthreads();
;     if ((tid & 63) == 0) scr[tid >> 6] = m;
;     __syncthreads();
;     float r = scr[0];
; #pragma unroll
;     for (int i = 1; i < NWAVES; ++i) r = fmaxf(r, scr[i]);
;     return r;
; __global__ void __launch_bounds__(NWAVES * 64, 2) fwd_kernel(Args args) {
;     ...
;         if (blockIdx.x == 0) {
;             LAS float* scr0 = (LAS float*)(F.lds + RING_OFF + 8 * 16384);
;             const float ca = 64.0f * QSCALE * att::wg_absmax(args.in[4], 192, scr0, F.tid) * att::wg_absmax(args.in[5], 192, scr0, F.tid) + LOG2E * att::wg_absmax(args.in[6], 48 * 32, scr0, F.tid);
;             const float cb = 64.0f * QSCALE * att::wg_absmax(args.in[9], 64, scr0, F.tid) * att::wg_absmax(args.in[10], 64, scr0, F.tid) + LOG2E * att::wg_absmax(args.in[11], NH * 15 * 31, scr0, F.tid);
;             if (F.tid == 0) { float* cs = (float*)(ws + WS_CSHIFT); cs[0] = ca; cs[1] = cb; }
.LBB0_63:
	s_waitcnt vmcnt(0)
	v_max_f32_e64 v24, |v118|, |v118|
	v_max_f32_e64 v25, |v119|, |v119|
	v_max_f32_e64 v26, |v120|, |v121|
	v_max_f32_e64 v27, |v123|, |v123|
	v_max_f32_e64 v28, |v124|, |v124|
	v_max_f32_e64 v29, |v125|, |v126|
	v_max_f32_e64 v26, v26, |v122|
	v_max_f32_e64 v29, v29, |v127|
	v_max_f32_e64 v29, v29, |v128|
	v_max_f32_e64 v29, v29, |v129|
	v_max_f32_e64 v29, v29, |v130|
	v_max_f32_e64 v29, v29, |v131|
	v_max_f32_e64 v29, v29, |v132|
	v_max_f32_e64 v29, v29, |v133|
	v_max_f32_e64 v29, v29, |v134|
	v_max_f32_e64 v29, v29, |v135|
	v_max_f32_e64 v29, v29, |v136|
	v_max_f32_e64 v29, v29, |v137|
	v_max_f32_e64 v29, v29, |v138|
	v_max_f32_e64 v29, v29, |v139|
	s_nop 1
	v_mov_b32_dpp v30, v24 quad_perm:[1,0,3,2] row_mask:0xf bank_mask:0xf bound_ctrl:1
	v_mov_b32_dpp v31, v25 quad_perm:[1,0,3,2] row_mask:0xf bank_mask:0xf bound_ctrl:1
	v_mov_b32_dpp v32, v26 quad_perm:[1,0,3,2] row_mask:0xf bank_mask:0xf bound_ctrl:1
	v_mov_b32_dpp v33, v27 quad_perm:[1,0,3,2] row_mask:0xf bank_mask:0xf bound_ctrl:1
	v_mov_b32_dpp v34, v28 quad_perm:[1,0,3,2] row_mask:0xf bank_mask:0xf bound_ctrl:1
	v_mov_b32_dpp v35, v29 quad_perm:[1,0,3,2] row_mask:0xf bank_mask:0xf bound_ctrl:1
	v_max_f32_e32 v24, v24, v30
	v_max_f32_e32 v25, v25, v31
	v_max_f32_e32 v26, v26, v32
	v_max_f32_e32 v27, v27, v33
	v_max_f32_e32 v28, v28, v34
	v_max_f32_e32 v29, v29, v35
	s_nop 1
	v_mov_b32_dpp v30, v24 quad_perm:[2,3,0,1] row_mask:0xf bank_mask:0xf bound_ctrl:1
	v_mov_b32_dpp v31, v25 quad_perm:[2,3,0,1] row_mask:0xf bank_mask:0xf bound_ctrl:1
	v_mov_b32_dpp v32, v26 quad_perm:[2,3,0,1] row_mask:0xf bank_mask:0xf bound_ctrl:1
	v_mov_b32_dpp v33, v27 quad_perm:[2,3,0,1] row_mask:0xf bank_mask:0xf bound_ctrl:1
	v_mov_b32_dpp v34, v28 quad_perm:[2,3,0,1] row_mask:0xf bank_mask:0xf bound_ctrl:1
	v_mov_b32_dpp v35, v29 quad_perm:[2,3,0,1] row_mask:0xf bank_mask:0xf bound_ctrl:1
	v_max_f32_e32 v24, v24, v30
	v_max_f32_e32 v25, v25, v31
	v_max_f32_e32 v26, v26, v32
	v_max_f32_e32 v27, v27, v33
	v_max_f32_e32 v28, v28, v34
	v_max_f32_e32 v29, v29, v35
	s_nop 1
	v_mov_b32_dpp v30, v24 row_half_mirror row_mask:0xf bank_mask:0xf bound_ctrl:1
	v_mov_b32_dpp v31, v25 row_half_mirror row_mask:0xf bank_mask:0xf bound_ctrl:1
	v_mov_b32_dpp v32, v26 row_half_mirror row_mask:0xf bank_mask:0xf bound_ctrl:1
	v_mov_b32_dpp v33, v27 row_half_mirror row_mask:0xf bank_mask:0xf bound_ctrl:1
	v_mov_b32_dpp v34, v28 row_half_mirror row_mask:0xf bank_mask:0xf bound_ctrl:1
	v_mov_b32_dpp v35, v29 row_half_mirror row_mask:0xf bank_mask:0xf bound_ctrl:1
	v_max_f32_e32 v24, v24, v30
	v_max_f32_e32 v25, v25, v31
	v_max_f32_e32 v26, v26, v32
	v_max_f32_e32 v27, v27, v33
	v_max_f32_e32 v28, v28, v34
	v_max_f32_e32 v29, v29, v35
	s_nop 1
	v_mov_b32_dpp v30, v24 row_mirror row_mask:0xf bank_mask:0xf bound_ctrl:1
	v_mov_b32_dpp v31, v25 row_mirror row_mask:0xf bank_mask:0xf bound_ctrl:1
	v_mov_b32_dpp v32, v26 row_mirror row_mask:0xf bank_mask:0xf bound_ctrl:1
	v_mov_b32_dpp v33, v27 row_mirror row_mask:0xf bank_mask:0xf bound_ctrl:1
	v_mov_b32_dpp v34, v28 row_mirror row_mask:0xf bank_mask:0xf bound_ctrl:1
	v_mov_b32_dpp v35, v29 row_mirror row_mask:0xf bank_mask:0xf bound_ctrl:1
	v_max_f32_e32 v24, v24, v30
	v_max_f32_e32 v25, v25, v31
	v_max_f32_e32 v26, v26, v32
	v_max_f32_e32 v27, v27, v33
	v_max_f32_e32 v28, v28, v34
	v_max_f32_e32 v29, v29, v35
	v_mov_b32_e32 v30, v24
	v_mov_b32_e32 v31, v25
	v_mov_b32_e32 v32, v26
	v_mov_b32_e32 v33, v27
	v_mov_b32_e32 v34, v28
	v_mov_b32_e32 v35, v29
	s_nop 1
	v_permlane16_swap_b32_e32 v24, v30
	v_permlane16_swap_b32_e32 v25, v31
	v_permlane16_swap_b32_e32 v26, v32
	v_permlane16_swap_b32_e32 v27, v33
	v_permlane16_swap_b32_e32 v28, v34
	v_permlane16_swap_b32_e32 v29, v35
	s_nop 1
	v_max_f32_e32 v24, v24, v30
	v_max_f32_e32 v25, v25, v31
	v_max_f32_e32 v26, v26, v32
	v_max_f32_e32 v27, v27, v33
	v_max_f32_e32 v28, v28, v34
	v_max_f32_e32 v29, v29, v35
	v_mov_b32_e32 v30, v24
	v_mov_b32_e32 v31, v25
	v_mov_b32_e32 v32, v26
	v_mov_b32_e32 v33, v27
	v_mov_b32_e32 v34, v28
	v_mov_b32_e32 v35, v29
	s_nop 1
	v_permlane32_swap_b32_e32 v24, v30
	v_permlane32_swap_b32_e32 v25, v31
	v_permlane32_swap_b32_e32 v26, v32
	v_permlane32_swap_b32_e32 v27, v33
	v_permlane32_swap_b32_e32 v28, v34
	v_permlane32_swap_b32_e32 v29, v35
	s_nop 1
	v_max_f32_e32 v24, v24, v30
	v_max_f32_e32 v25, v25, v31
	v_max_f32_e32 v26, v26, v32
	v_max_f32_e32 v27, v27, v33
	v_max_f32_e32 v28, v28, v34
	v_max_f32_e32 v29, v29, v35
	v_and_b32_e32 v36, 63, v64
	v_lshrrev_b32_e32 v37, 6, v64
	v_lshlrev_b32_e32 v37, 2, v37
	v_add_u32_e32 v37, 0x20000, v37
	v_cmp_eq_u32_e32 vcc, 0, v36
	s_and_saveexec_b64 s[0:1], vcc
	ds_write_b32 v37, v24
	ds_write_b32 v37, v25 offset:32
	ds_write_b32 v37, v26 offset:64
	ds_write_b32 v37, v27 offset:96
	ds_write_b32 v37, v28 offset:128
	ds_write_b32 v37, v29 offset:160
	s_mov_b64 exec, s[0:1]
	s_waitcnt lgkmcnt(0)
	s_barrier
	v_mov_b32_e32 v48, 0x20000
	ds_read_b128 v[0:3], v48
	ds_read_b128 v[4:7], v48 offset:16
	ds_read_b128 v[8:11], v48 offset:32
	ds_read_b128 v[12:15], v48 offset:48
	ds_read_b128 v[16:19], v48 offset:64
	ds_read_b128 v[20:23], v48 offset:80
	ds_read_b128 v[24:27], v48 offset:96
	ds_read_b128 v[28:31], v48 offset:112
	ds_read_b128 v[32:35], v48 offset:128
	ds_read_b128 v[36:39], v48 offset:144
	ds_read_b128 v[40:43], v48 offset:160
	ds_read_b128 v[44:47], v48 offset:176
	s_waitcnt lgkmcnt(0)
	v_max3_f32 v0, v0, v1, v2
	v_max3_f32 v4, v3, v4, v5
	v_max3_f32 v0, v0, v6, v7
	v_max_f32_e32 v0, v0, v4
	v_max3_f32 v8, v8, v9, v10
	v_max3_f32 v12, v11, v12, v13
	v_max3_f32 v8, v8, v14, v15
	v_max_f32_e32 v8, v8, v12
	v_max3_f32 v16, v16, v17, v18
	v_max3_f32 v20, v19, v20, v21
	v_max3_f32 v16, v16, v22, v23
	v_max_f32_e32 v16, v16, v20
	v_max3_f32 v24, v24, v25, v26
	v_max3_f32 v28, v27, v28, v29
	v_max3_f32 v24, v24, v30, v31
	v_max_f32_e32 v24, v24, v28
	v_max3_f32 v32, v32, v33, v34
	v_max3_f32 v36, v35, v36, v37
	v_max3_f32 v32, v32, v38, v39
	v_max_f32_e32 v32, v32, v36
	v_max3_f32 v40, v40, v41, v42
	v_max3_f32 v44, v43, v44, v45
	v_max3_f32 v40, v40, v46, v47
	v_max_f32_e32 v40, v40, v44
	v_mul_f32_e32 v0, 0x4138aa3b, v0
	v_mul_f32_e32 v24, 0x4138aa3b, v24
	v_mul_f32_e32 v16, 0x3fb8aa3b, v16
	v_mul_f32_e32 v40, 0x3fb8aa3b, v40
	v_fma_f32 v0, v0, v8, v16
	v_fma_f32 v1, v24, v32, v40
	v_readlane_b32 s4, v253, 20
	v_readlane_b32 s5, v253, 21
	v_mov_b32_e32 v2, 0
	v_cmp_eq_u32_e32 vcc, 0, v64
	s_and_saveexec_b64 s[0:1], vcc
	s_nop 3
	global_store_dwordx2 v2, v[0:1], s[4:5]
